# stack2 plus: A attention tile loop stages K/V in place, no phi copies and no vmcnt(0) drain of the just-issued prefetch (counted vmcnt(2) wait)
# speedup vs baseline: 1.0013x; 1.0013x over previous
; #define ISSUE(t, KR, VR) do { const GAS bf16_t* tb_ = (const GAS bf16_t*)Z + (size_t)TILE_ROW(t) * ZW; \
;         KR[0] = *(const GAS u32x4*)(tb_ + koff); KR[1] = *(const GAS u32x4*)(tb_ + koff + 64); \
;         VR[0] = *(const GAS u32x4*)(tb_ + voff); VR[1] = *(const GAS u32x4*)(tb_ + voff + ZW); } while (0)
; template <int MODE>
; DI void attn_unit(const Ctx& C, const bf16_t* __restrict__ Z, bf16_t* __restrict__ Y, int b, int qsel, int hsel, bool ctxq,
;                   const float* sinkp, const float* rpb_h, float lam, float post_scale, const float* subln, const float mref) {
;     ...
;     for (int t = 0; t < nt; ++t) {
;         if (t + 1 < nt) {
;             if ((t + 1) & 1) { WRITE(1, kB, vB); if (t + 3 < nt) ISSUE(t + 3, kB, vB); }
;             else { WRITE(0, kA, vA); if (t + 3 < nt) ISSUE(t + 3, kA, vA); }
;         }
.LBB0_430:
	s_add_i32 s29, s28, 9
	s_add_i32 s6, s28, 10
	s_cmp_ge_i32 s6, s21
	s_cbranch_scc1 .LBB0_439
	s_cmp_le_i32 s29, s20
	s_cselect_b64 s[6:7], -1, 0
	s_add_i32 s14, s20, 1
	s_cmp_le_i32 s29, s14
	s_cbranch_scc1 .Laphi_w2
	s_waitcnt vmcnt(0)
	s_branch .Laphi_go

; #define ISSUE(t, KR, VR) do { const GAS bf16_t* tb_ = (const GAS bf16_t*)Z + (size_t)TILE_ROW(t) * ZW; \
;         KR[0] = *(const GAS u32x4*)(tb_ + koff); KR[1] = *(const GAS u32x4*)(tb_ + koff + 64); \
;         VR[0] = *(const GAS u32x4*)(tb_ + voff); VR[1] = *(const GAS u32x4*)(tb_ + voff + ZW); } while (0)
; template <int MODE>
; DI void attn_unit(const Ctx& C, const bf16_t* __restrict__ Z, bf16_t* __restrict__ Y, int b, int qsel, int hsel, bool ctxq,
;                   const float* sinkp, const float* rpb_h, float lam, float post_scale, const float* subln, const float mref) {
;     ...
;     for (int t = 0; t < nt; ++t) {
;         if (t + 1 < nt) {
;             if ((t + 1) & 1) { WRITE(1, kB, vB); if (t + 3 < nt) ISSUE(t + 3, kB, vB); }
;             else { WRITE(0, kA, vA); if (t + 3 < nt) ISSUE(t + 3, kA, vA); }
;         }
.Laphi_go:
	s_bitcmp1_b32 s29, 0
	s_cbranch_scc0 .Laphi_even
	ds_write_b128 v142, v[40:43]
	ds_write_b16 v143, v44 offset:9216
	ds_write_b16_d16_hi v143, v44 offset:9360
	ds_write_b16 v143, v45 offset:9504
	ds_write_b16_d16_hi v143, v45 offset:9648
	ds_write_b16 v143, v46 offset:9792
	ds_write_b16_d16_hi v143, v46 offset:9936
	ds_write_b16 v143, v47 offset:10080
	ds_write_b16_d16_hi v143, v47 offset:10224
	s_and_b64 vcc, exec, s[6:7]
	s_cbranch_vccz .LBB0_439
	s_add_i32 s14, s19, s24
	s_mul_hi_i32 s15, s14, 0x2200
	s_mulk_i32 s14, 0x2200
	s_add_u32 s14, s8, s14
	s_addc_u32 s15, s9, s15
	v_lshl_add_u64 v[88:89], v[0:1], 1, s[14:15]
	v_lshl_add_u64 v[92:93], v[2:3], 1, s[14:15]
	global_load_dwordx4 v[40:43], v[88:89], off
	global_load_dwordx4 v[44:47], v[92:93], off
	s_branch .LBB0_439
.Laphi_even:
	ds_write_b128 v142, v[48:51] offset:36864
	ds_write_b16 v143, v52 offset:46080
	ds_write_b16_d16_hi v143, v52 offset:46224
	ds_write_b16 v143, v53 offset:46368
	ds_write_b16_d16_hi v143, v53 offset:46512
	ds_write_b16 v143, v54 offset:46656
	ds_write_b16_d16_hi v143, v54 offset:46800
	ds_write_b16 v143, v55 offset:46944
	ds_write_b16_d16_hi v143, v55 offset:47088
	s_and_b64 vcc, exec, s[6:7]
	s_cbranch_vccz .LBB0_439
	s_add_i32 s6, s19, s24
	s_mul_hi_i32 s7, s6, 0x2200
	s_mulk_i32 s6, 0x2200
	s_add_u32 s6, s8, s6
	s_addc_u32 s7, s9, s7
	v_lshl_add_u64 v[88:89], v[0:1], 1, s[6:7]
	v_lshl_add_u64 v[92:93], v[2:3], 1, s[6:7]
	global_load_dwordx4 v[48:51], v[88:89], off
	global_load_dwordx4 v[52:55], v[92:93], off
